# EpiResid epilogues (P7 w_out, P11 w_down): 16 x_in loads in flight with counted vmcnt instead of 32 load->vmcnt(0)->store round trips
# speedup vs baseline: 1.0143x; 1.0143x over previous
.LBB0_891:
	s_lshl_b64 s[24:25], s[26:27], 2
	s_add_u32 s24, s30, s24
	s_addc_u32 s25, s31, s25
	s_add_u32 s24, s24, 0x2000
	s_addc_u32 s25, s25, 0
	v_lshlrev_b32_e32 v142, 2, v140
	v_add_u32_e32 v143, s54, v166
	v_lshl_add_u32 v143, v143, 12, v142
	global_load_dwordx4 v[212:215], v142, s[24:25]
	global_load_dwordx4 v[216:219], v142, s[24:25] offset:64
	global_load_dwordx4 v[220:223], v142, s[24:25] offset:512
	global_load_dwordx4 v[224:227], v142, s[24:25] offset:576
	s_add_u32 s28, s20, 0x0
	s_addc_u32 s29, s21, 0
	global_load_dwordx4 v[144:147], v143, s[28:29]
	global_load_dwordx4 v[148:151], v143, s[28:29] offset:64
	global_load_dwordx4 v[152:155], v143, s[28:29] offset:512
	global_load_dwordx4 v[156:159], v143, s[28:29] offset:576
	s_add_u32 s28, s20, 0x10000
	s_addc_u32 s29, s21, 0
	global_load_dwordx4 v[168:171], v143, s[28:29]
	global_load_dwordx4 v[172:175], v143, s[28:29] offset:64
	global_load_dwordx4 v[176:179], v143, s[28:29] offset:512
	global_load_dwordx4 v[186:189], v143, s[28:29] offset:576
	s_add_u32 s28, s20, 0x20000
	s_addc_u32 s29, s21, 0
	global_load_dwordx4 v[190:193], v143, s[28:29]
	global_load_dwordx4 v[228:231], v143, s[28:29] offset:64
	global_load_dwordx4 v[232:235], v143, s[28:29] offset:512
	global_load_dwordx4 v[236:239], v143, s[28:29] offset:576
	s_add_u32 s28, s20, 0x30000
	s_addc_u32 s29, s21, 0
	global_load_dwordx4 v[240:243], v143, s[28:29]
	global_load_dwordx4 v[244:247], v143, s[28:29] offset:64
	global_load_dwordx4 v[248:251], v143, s[28:29] offset:512
	global_load_dwordx4 v[130:133], v143, s[28:29] offset:576
	s_waitcnt vmcnt(12)
	v_pk_fma_f32 v[126:127], v[126:127], v[212:213], v[144:145]
	v_pk_fma_f32 v[128:129], v[128:129], v[214:215], v[146:147]
	v_pk_fma_f32 v[102:103], v[102:103], v[216:217], v[148:149]
	v_pk_fma_f32 v[104:105], v[104:105], v[218:219], v[150:151]
	v_pk_fma_f32 v[74:75], v[74:75], v[220:221], v[152:153]
	v_pk_fma_f32 v[76:77], v[76:77], v[222:223], v[154:155]
	v_pk_fma_f32 v[46:47], v[46:47], v[224:225], v[156:157]
	v_pk_fma_f32 v[48:49], v[48:49], v[226:227], v[158:159]
	s_add_u32 s28, s20, 0x80000
	s_addc_u32 s29, s21, 0
	global_load_dwordx4 v[144:147], v143, s[28:29]
	global_load_dwordx4 v[148:151], v143, s[28:29] offset:64
	global_load_dwordx4 v[152:155], v143, s[28:29] offset:512
	global_load_dwordx4 v[156:159], v143, s[28:29] offset:576
	s_add_u32 s24, s22, 0x0
	s_addc_u32 s25, s23, 0
	global_store_dwordx4 v143, v[126:129], s[24:25]
	global_store_dwordx4 v143, v[102:105], s[24:25] offset:64
	global_store_dwordx4 v143, v[74:77], s[24:25] offset:512
	global_store_dwordx4 v143, v[46:49], s[24:25] offset:576
	s_waitcnt vmcnt(16)
	v_pk_fma_f32 v[122:123], v[122:123], v[212:213], v[168:169]
	v_pk_fma_f32 v[124:125], v[124:125], v[214:215], v[170:171]
	v_pk_fma_f32 v[94:95], v[94:95], v[216:217], v[172:173]
	v_pk_fma_f32 v[96:97], v[96:97], v[218:219], v[174:175]
	v_pk_fma_f32 v[66:67], v[66:67], v[220:221], v[176:177]
	v_pk_fma_f32 v[68:69], v[68:69], v[222:223], v[178:179]
	v_pk_fma_f32 v[38:39], v[38:39], v[224:225], v[186:187]
	v_pk_fma_f32 v[40:41], v[40:41], v[226:227], v[188:189]
	s_add_u32 s28, s20, 0x90000
	s_addc_u32 s29, s21, 0
	global_load_dwordx4 v[168:171], v143, s[28:29]
	global_load_dwordx4 v[172:175], v143, s[28:29] offset:64
	global_load_dwordx4 v[176:179], v143, s[28:29] offset:512
	global_load_dwordx4 v[186:189], v143, s[28:29] offset:576
	s_add_u32 s24, s22, 0x10000
	s_addc_u32 s25, s23, 0
	global_store_dwordx4 v143, v[122:125], s[24:25]
	global_store_dwordx4 v143, v[94:97], s[24:25] offset:64
	global_store_dwordx4 v143, v[66:69], s[24:25] offset:512
	global_store_dwordx4 v143, v[38:41], s[24:25] offset:576
	s_waitcnt vmcnt(20)
	v_pk_fma_f32 v[118:119], v[118:119], v[212:213], v[190:191]
	v_pk_fma_f32 v[120:121], v[120:121], v[214:215], v[192:193]
	v_pk_fma_f32 v[90:91], v[90:91], v[216:217], v[228:229]
	v_pk_fma_f32 v[92:93], v[92:93], v[218:219], v[230:231]
	v_pk_fma_f32 v[58:59], v[58:59], v[220:221], v[232:233]
	v_pk_fma_f32 v[60:61], v[60:61], v[222:223], v[234:235]
	v_pk_fma_f32 v[30:31], v[30:31], v[224:225], v[236:237]
	v_pk_fma_f32 v[32:33], v[32:33], v[226:227], v[238:239]
	s_add_u32 s28, s20, 0xa0000
	s_addc_u32 s29, s21, 0
	global_load_dwordx4 v[190:193], v143, s[28:29]
	global_load_dwordx4 v[228:231], v143, s[28:29] offset:64
	global_load_dwordx4 v[232:235], v143, s[28:29] offset:512
	global_load_dwordx4 v[236:239], v143, s[28:29] offset:576
	s_add_u32 s24, s22, 0x20000
	s_addc_u32 s25, s23, 0
	global_store_dwordx4 v143, v[118:121], s[24:25]
	global_store_dwordx4 v143, v[90:93], s[24:25] offset:64
	global_store_dwordx4 v143, v[58:61], s[24:25] offset:512
	global_store_dwordx4 v143, v[30:33], s[24:25] offset:576
	s_waitcnt vmcnt(24)
	v_pk_fma_f32 v[114:115], v[114:115], v[212:213], v[240:241]
	v_pk_fma_f32 v[116:117], v[116:117], v[214:215], v[242:243]
	v_pk_fma_f32 v[86:87], v[86:87], v[216:217], v[244:245]
	v_pk_fma_f32 v[88:89], v[88:89], v[218:219], v[246:247]
	v_pk_fma_f32 v[50:51], v[50:51], v[220:221], v[248:249]
	v_pk_fma_f32 v[52:53], v[52:53], v[222:223], v[250:251]
	v_pk_fma_f32 v[22:23], v[22:23], v[224:225], v[130:131]
	v_pk_fma_f32 v[24:25], v[24:25], v[226:227], v[132:133]
	s_add_u32 s28, s20, 0xb0000
	s_addc_u32 s29, s21, 0
	global_load_dwordx4 v[240:243], v143, s[28:29]
	global_load_dwordx4 v[244:247], v143, s[28:29] offset:64
	global_load_dwordx4 v[248:251], v143, s[28:29] offset:512
	global_load_dwordx4 v[130:133], v143, s[28:29] offset:576
	s_add_u32 s24, s22, 0x30000
	s_addc_u32 s25, s23, 0
	global_store_dwordx4 v143, v[114:117], s[24:25]
	global_store_dwordx4 v143, v[86:89], s[24:25] offset:64
	global_store_dwordx4 v143, v[50:53], s[24:25] offset:512
	global_store_dwordx4 v143, v[22:25], s[24:25] offset:576
	s_waitcnt vmcnt(28)
	v_pk_fma_f32 v[110:111], v[110:111], v[212:213], v[144:145]
	v_pk_fma_f32 v[112:113], v[112:113], v[214:215], v[146:147]
	v_pk_fma_f32 v[78:79], v[78:79], v[216:217], v[148:149]
	v_pk_fma_f32 v[80:81], v[80:81], v[218:219], v[150:151]
	v_pk_fma_f32 v[42:43], v[42:43], v[220:221], v[152:153]
	v_pk_fma_f32 v[44:45], v[44:45], v[222:223], v[154:155]
	v_pk_fma_f32 v[14:15], v[14:15], v[224:225], v[156:157]
	v_pk_fma_f32 v[16:17], v[16:17], v[226:227], v[158:159]
	s_add_u32 s24, s22, 0x80000
	s_addc_u32 s25, s23, 0
	global_store_dwordx4 v143, v[110:113], s[24:25]
	global_store_dwordx4 v143, v[78:81], s[24:25] offset:64
	global_store_dwordx4 v143, v[42:45], s[24:25] offset:512
	global_store_dwordx4 v143, v[14:17], s[24:25] offset:576
	s_waitcnt vmcnt(24)
	v_pk_fma_f32 v[106:107], v[106:107], v[212:213], v[168:169]
	v_pk_fma_f32 v[108:109], v[108:109], v[214:215], v[170:171]
	v_pk_fma_f32 v[70:71], v[70:71], v[216:217], v[172:173]
	v_pk_fma_f32 v[72:73], v[72:73], v[218:219], v[174:175]
	v_pk_fma_f32 v[34:35], v[34:35], v[220:221], v[176:177]
	v_pk_fma_f32 v[36:37], v[36:37], v[222:223], v[178:179]
	v_pk_fma_f32 v[10:11], v[10:11], v[224:225], v[186:187]
	v_pk_fma_f32 v[12:13], v[12:13], v[226:227], v[188:189]
	s_add_u32 s24, s22, 0x90000
	s_addc_u32 s25, s23, 0
	global_store_dwordx4 v143, v[106:109], s[24:25]
	global_store_dwordx4 v143, v[70:73], s[24:25] offset:64
	global_store_dwordx4 v143, v[34:37], s[24:25] offset:512
	global_store_dwordx4 v143, v[10:13], s[24:25] offset:576
	s_waitcnt vmcnt(20)
	v_pk_fma_f32 v[98:99], v[98:99], v[212:213], v[190:191]
	v_pk_fma_f32 v[100:101], v[100:101], v[214:215], v[192:193]
	v_pk_fma_f32 v[62:63], v[62:63], v[216:217], v[228:229]
	v_pk_fma_f32 v[64:65], v[64:65], v[218:219], v[230:231]
	v_pk_fma_f32 v[26:27], v[26:27], v[220:221], v[232:233]
	v_pk_fma_f32 v[28:29], v[28:29], v[222:223], v[234:235]
	v_pk_fma_f32 v[6:7], v[6:7], v[224:225], v[236:237]
	v_pk_fma_f32 v[8:9], v[8:9], v[226:227], v[238:239]
	s_add_u32 s24, s22, 0xa0000
	s_addc_u32 s25, s23, 0
	global_store_dwordx4 v143, v[98:101], s[24:25]
	global_store_dwordx4 v143, v[62:65], s[24:25] offset:64
	global_store_dwordx4 v143, v[26:29], s[24:25] offset:512
	global_store_dwordx4 v143, v[6:9], s[24:25] offset:576
	s_waitcnt vmcnt(16)
	v_pk_fma_f32 v[82:83], v[82:83], v[212:213], v[240:241]
	v_pk_fma_f32 v[84:85], v[84:85], v[214:215], v[242:243]
	v_pk_fma_f32 v[54:55], v[54:55], v[216:217], v[244:245]
	v_pk_fma_f32 v[56:57], v[56:57], v[218:219], v[246:247]
	v_pk_fma_f32 v[18:19], v[18:19], v[220:221], v[248:249]
	v_pk_fma_f32 v[20:21], v[20:21], v[222:223], v[250:251]
	v_pk_fma_f32 v[2:3], v[2:3], v[224:225], v[130:131]
	v_pk_fma_f32 v[4:5], v[4:5], v[226:227], v[132:133]
	s_add_u32 s24, s22, 0xb0000
	s_addc_u32 s25, s23, 0
	global_store_dwordx4 v143, v[82:85], s[24:25]
	global_store_dwordx4 v143, v[54:57], s[24:25] offset:64
	global_store_dwordx4 v143, v[18:21], s[24:25] offset:512
	global_store_dwordx4 v143, v[2:5], s[24:25] offset:576
	s_and_b64 vcc, exec, s[42:43]
	s_mov_b64 s[20:21], -1
	s_cbranch_vccnz .LBB0_870
	s_branch .LBB0_894

.LBB0_1223:
	s_lshl_b64 s[14:15], s[20:21], 2
	s_add_u32 s14, s30, s14
	s_addc_u32 s15, s31, s15
	s_add_u32 s14, s14, 0x5000
	s_addc_u32 s15, s15, 0
	v_lshlrev_b32_e32 v171, 2, v144
	v_add_u32_e32 v180, s43, v170
	v_lshl_add_u32 v180, v180, 12, v171
	global_load_dwordx4 v[212:215], v171, s[14:15]
	global_load_dwordx4 v[216:219], v171, s[14:15] offset:64
	global_load_dwordx4 v[220:223], v171, s[14:15] offset:512
	global_load_dwordx4 v[224:227], v171, s[14:15] offset:576
	s_add_u32 s22, s18, 0x0
	s_addc_u32 s23, s19, 0
	global_load_dwordx4 v[146:149], v180, s[22:23]
	global_load_dwordx4 v[150:153], v180, s[22:23] offset:64
	global_load_dwordx4 v[154:157], v180, s[22:23] offset:512
	global_load_dwordx4 v[158:161], v180, s[22:23] offset:576
	s_add_u32 s22, s18, 0x10000
	s_addc_u32 s23, s19, 0
	global_load_dwordx4 v[162:165], v180, s[22:23]
	global_load_dwordx4 v[172:175], v180, s[22:23] offset:64
	global_load_dwordx4 v[176:179], v180, s[22:23] offset:512
	global_load_dwordx4 v[186:189], v180, s[22:23] offset:576
	s_add_u32 s22, s18, 0x20000
	s_addc_u32 s23, s19, 0
	global_load_dwordx4 v[190:193], v180, s[22:23]
	global_load_dwordx4 v[228:231], v180, s[22:23] offset:64
	global_load_dwordx4 v[232:235], v180, s[22:23] offset:512
	global_load_dwordx4 v[236:239], v180, s[22:23] offset:576
	s_add_u32 s22, s18, 0x30000
	s_addc_u32 s23, s19, 0
	global_load_dwordx4 v[240:243], v180, s[22:23]
	global_load_dwordx4 v[244:247], v180, s[22:23] offset:64
	global_load_dwordx4 v[248:251], v180, s[22:23] offset:512
	global_load_dwordx4 v[130:133], v180, s[22:23] offset:576
	s_waitcnt vmcnt(12)
	v_pk_fma_f32 v[126:127], v[126:127], v[212:213], v[146:147]
	v_pk_fma_f32 v[128:129], v[128:129], v[214:215], v[148:149]
	v_pk_fma_f32 v[98:99], v[98:99], v[216:217], v[150:151]
	v_pk_fma_f32 v[100:101], v[100:101], v[218:219], v[152:153]
	v_pk_fma_f32 v[66:67], v[66:67], v[220:221], v[154:155]
	v_pk_fma_f32 v[68:69], v[68:69], v[222:223], v[156:157]
	v_pk_fma_f32 v[38:39], v[38:39], v[224:225], v[158:159]
	v_pk_fma_f32 v[40:41], v[40:41], v[226:227], v[160:161]
	s_add_u32 s22, s18, 0x80000
	s_addc_u32 s23, s19, 0
	global_load_dwordx4 v[146:149], v180, s[22:23]
	global_load_dwordx4 v[150:153], v180, s[22:23] offset:64
	global_load_dwordx4 v[154:157], v180, s[22:23] offset:512
	global_load_dwordx4 v[158:161], v180, s[22:23] offset:576
	s_add_u32 s14, s18, 0x0
	s_addc_u32 s15, s19, 0
	global_store_dwordx4 v180, v[126:129], s[14:15]
	global_store_dwordx4 v180, v[98:101], s[14:15] offset:64
	global_store_dwordx4 v180, v[66:69], s[14:15] offset:512
	global_store_dwordx4 v180, v[38:41], s[14:15] offset:576
	s_waitcnt vmcnt(16)
	v_pk_fma_f32 v[122:123], v[122:123], v[212:213], v[162:163]
	v_pk_fma_f32 v[124:125], v[124:125], v[214:215], v[164:165]
	v_pk_fma_f32 v[94:95], v[94:95], v[216:217], v[172:173]
	v_pk_fma_f32 v[96:97], v[96:97], v[218:219], v[174:175]
	v_pk_fma_f32 v[62:63], v[62:63], v[220:221], v[176:177]
	v_pk_fma_f32 v[64:65], v[64:65], v[222:223], v[178:179]
	v_pk_fma_f32 v[30:31], v[30:31], v[224:225], v[186:187]
	v_pk_fma_f32 v[32:33], v[32:33], v[226:227], v[188:189]
	s_add_u32 s22, s18, 0x90000
	s_addc_u32 s23, s19, 0
	global_load_dwordx4 v[162:165], v180, s[22:23]
	global_load_dwordx4 v[172:175], v180, s[22:23] offset:64
	global_load_dwordx4 v[176:179], v180, s[22:23] offset:512
	global_load_dwordx4 v[186:189], v180, s[22:23] offset:576
	s_add_u32 s14, s18, 0x10000
	s_addc_u32 s15, s19, 0
	global_store_dwordx4 v180, v[122:125], s[14:15]
	global_store_dwordx4 v180, v[94:97], s[14:15] offset:64
	global_store_dwordx4 v180, v[62:65], s[14:15] offset:512
	global_store_dwordx4 v180, v[30:33], s[14:15] offset:576
	s_waitcnt vmcnt(20)
	v_pk_fma_f32 v[118:119], v[118:119], v[212:213], v[190:191]
	v_pk_fma_f32 v[120:121], v[120:121], v[214:215], v[192:193]
	v_pk_fma_f32 v[86:87], v[86:87], v[216:217], v[228:229]
	v_pk_fma_f32 v[88:89], v[88:89], v[218:219], v[230:231]
	v_pk_fma_f32 v[54:55], v[54:55], v[220:221], v[232:233]
	v_pk_fma_f32 v[56:57], v[56:57], v[222:223], v[234:235]
	v_pk_fma_f32 v[22:23], v[22:23], v[224:225], v[236:237]
	v_pk_fma_f32 v[24:25], v[24:25], v[226:227], v[238:239]
	s_add_u32 s22, s18, 0xa0000
	s_addc_u32 s23, s19, 0
	global_load_dwordx4 v[190:193], v180, s[22:23]
	global_load_dwordx4 v[228:231], v180, s[22:23] offset:64
	global_load_dwordx4 v[232:235], v180, s[22:23] offset:512
	global_load_dwordx4 v[236:239], v180, s[22:23] offset:576
	s_add_u32 s14, s18, 0x20000
	s_addc_u32 s15, s19, 0
	global_store_dwordx4 v180, v[118:121], s[14:15]
	global_store_dwordx4 v180, v[86:89], s[14:15] offset:64
	global_store_dwordx4 v180, v[54:57], s[14:15] offset:512
	global_store_dwordx4 v180, v[22:25], s[14:15] offset:576
	s_waitcnt vmcnt(24)
	v_pk_fma_f32 v[114:115], v[114:115], v[212:213], v[240:241]
	v_pk_fma_f32 v[116:117], v[116:117], v[214:215], v[242:243]
	v_pk_fma_f32 v[82:83], v[82:83], v[216:217], v[244:245]
	v_pk_fma_f32 v[84:85], v[84:85], v[218:219], v[246:247]
	v_pk_fma_f32 v[50:51], v[50:51], v[220:221], v[248:249]
	v_pk_fma_f32 v[52:53], v[52:53], v[222:223], v[250:251]
	v_pk_fma_f32 v[18:19], v[18:19], v[224:225], v[130:131]
	v_pk_fma_f32 v[20:21], v[20:21], v[226:227], v[132:133]
	s_add_u32 s22, s18, 0xb0000
	s_addc_u32 s23, s19, 0
	global_load_dwordx4 v[240:243], v180, s[22:23]
	global_load_dwordx4 v[244:247], v180, s[22:23] offset:64
	global_load_dwordx4 v[248:251], v180, s[22:23] offset:512
	global_load_dwordx4 v[130:133], v180, s[22:23] offset:576
	s_add_u32 s14, s18, 0x30000
	s_addc_u32 s15, s19, 0
	global_store_dwordx4 v180, v[114:117], s[14:15]
	global_store_dwordx4 v180, v[82:85], s[14:15] offset:64
	global_store_dwordx4 v180, v[50:53], s[14:15] offset:512
	global_store_dwordx4 v180, v[18:21], s[14:15] offset:576
	s_waitcnt vmcnt(28)
	v_pk_fma_f32 v[110:111], v[110:111], v[212:213], v[146:147]
	v_pk_fma_f32 v[112:113], v[112:113], v[214:215], v[148:149]
	v_pk_fma_f32 v[78:79], v[78:79], v[216:217], v[150:151]
	v_pk_fma_f32 v[80:81], v[80:81], v[218:219], v[152:153]
	v_pk_fma_f32 v[46:47], v[46:47], v[220:221], v[154:155]
	v_pk_fma_f32 v[48:49], v[48:49], v[222:223], v[156:157]
	v_pk_fma_f32 v[14:15], v[14:15], v[224:225], v[158:159]
	v_pk_fma_f32 v[16:17], v[16:17], v[226:227], v[160:161]
	s_add_u32 s14, s18, 0x80000
	s_addc_u32 s15, s19, 0
	global_store_dwordx4 v180, v[110:113], s[14:15]
	global_store_dwordx4 v180, v[78:81], s[14:15] offset:64
	global_store_dwordx4 v180, v[46:49], s[14:15] offset:512
	global_store_dwordx4 v180, v[14:17], s[14:15] offset:576
	s_waitcnt vmcnt(24)
	v_pk_fma_f32 v[106:107], v[106:107], v[212:213], v[162:163]
	v_pk_fma_f32 v[108:109], v[108:109], v[214:215], v[164:165]
	v_pk_fma_f32 v[74:75], v[74:75], v[216:217], v[172:173]
	v_pk_fma_f32 v[76:77], v[76:77], v[218:219], v[174:175]
	v_pk_fma_f32 v[42:43], v[42:43], v[220:221], v[176:177]
	v_pk_fma_f32 v[44:45], v[44:45], v[222:223], v[178:179]
	v_pk_fma_f32 v[10:11], v[10:11], v[224:225], v[186:187]
	v_pk_fma_f32 v[12:13], v[12:13], v[226:227], v[188:189]
	s_add_u32 s14, s18, 0x90000
	s_addc_u32 s15, s19, 0
	global_store_dwordx4 v180, v[106:109], s[14:15]
	global_store_dwordx4 v180, v[74:77], s[14:15] offset:64
	global_store_dwordx4 v180, v[42:45], s[14:15] offset:512
	global_store_dwordx4 v180, v[10:13], s[14:15] offset:576
	s_waitcnt vmcnt(20)
	v_pk_fma_f32 v[102:103], v[102:103], v[212:213], v[190:191]
	v_pk_fma_f32 v[104:105], v[104:105], v[214:215], v[192:193]
	v_pk_fma_f32 v[70:71], v[70:71], v[216:217], v[228:229]
	v_pk_fma_f32 v[72:73], v[72:73], v[218:219], v[230:231]
	v_pk_fma_f32 v[34:35], v[34:35], v[220:221], v[232:233]
	v_pk_fma_f32 v[36:37], v[36:37], v[222:223], v[234:235]
	v_pk_fma_f32 v[6:7], v[6:7], v[224:225], v[236:237]
	v_pk_fma_f32 v[8:9], v[8:9], v[226:227], v[238:239]
	s_add_u32 s14, s18, 0xa0000
	s_addc_u32 s15, s19, 0
	global_store_dwordx4 v180, v[102:105], s[14:15]
	global_store_dwordx4 v180, v[70:73], s[14:15] offset:64
	global_store_dwordx4 v180, v[34:37], s[14:15] offset:512
	global_store_dwordx4 v180, v[6:9], s[14:15] offset:576
	s_waitcnt vmcnt(16)
	v_pk_fma_f32 v[90:91], v[90:91], v[212:213], v[240:241]
	v_pk_fma_f32 v[92:93], v[92:93], v[214:215], v[242:243]
	v_pk_fma_f32 v[58:59], v[58:59], v[216:217], v[244:245]
	v_pk_fma_f32 v[60:61], v[60:61], v[218:219], v[246:247]
	v_pk_fma_f32 v[26:27], v[26:27], v[220:221], v[248:249]
	v_pk_fma_f32 v[28:29], v[28:29], v[222:223], v[250:251]
	v_pk_fma_f32 v[2:3], v[2:3], v[224:225], v[130:131]
	v_pk_fma_f32 v[4:5], v[4:5], v[226:227], v[132:133]
	s_add_u32 s14, s18, 0xb0000
	s_addc_u32 s15, s19, 0
	global_store_dwordx4 v180, v[90:93], s[14:15]
	global_store_dwordx4 v180, v[58:61], s[14:15] offset:64
	global_store_dwordx4 v180, v[26:29], s[14:15] offset:512
	global_store_dwordx4 v180, v[2:5], s[14:15] offset:576
	s_and_b64 vcc, exec, s[40:41]
	s_mov_b64 s[14:15], -1
	s_cbranch_vccnz .LBB0_1202
	s_branch .LBB0_1226
